# act, p@w_ple_proj and final output stores written through (consumers re-read them after the L2 has turned over anyway)
# baseline (speedup 1.0000x reference)
; __device__ __forceinline__ unsigned cvt_pk_bf16(float lo, float hi) { unsigned r; asm("v_cvt_pk_bf16_f32 %0, %1, %2" : "=v"(r) : "v"(lo), "v"(hi)); return r; }
;     __device__ __forceinline__ void operator()(const Acc& acc, const Unit& u, int wr, int wc, int fr, int fq) const {
;         const int row0 = u.pm * BM + wr * 64 + fr, col0 = u.pn * HALF + wc * 32 + 8 * fq;
;         float rrv[8];
; #pragma unroll
;         for (int q = 0; q < 8; ++q) rrv[q] = lr[wr * 64 + fr + (q >> 2) * HALF + (q & 3) * 16];
; #pragma unroll
;         for (int ai = 0; ai < 2; ++ai)
; #pragma unroll
;             for (int m = 0; m < 4; ++m) {
;                 const int row = row0 + ai * HALF + m * 16;
;                 const float rr = rrv[ai * 4 + m];
;                 float r[8];
; #pragma unroll
;                 for (int n = 0; n < 2; ++n)
; #pragma unroll
;                     for (int j = 0; j < 4; ++j) {
;                         const float g = acc[ai][0][m][n][j] * rr, up = acc[ai][1][m][n][j] * rr;
;                         r[n * 4 + j] = g * __builtin_amdgcn_rcpf(1.f + __builtin_amdgcn_exp2f(-g * LOG2E)) * up;
;                     }
;                 u32x4 w; w.x = cvt_pk_bf16(r[0], r[1]); w.y = cvt_pk_bf16(r[2], r[3]); w.z = cvt_pk_bf16(r[4], r[5]); w.w = cvt_pk_bf16(r[6], r[7]);
;                 *(u32x4*)(O + (size_t)row * DFF + col0) = w;
;             }
.LBB0_684:
	ds_read2_b32 v[144:145], v150 offset1:16
	ds_read2_b32 v[142:143], v150 offset0:32 offset1:48
	ds_read2_b32 v[140:141], v150 offset0:128 offset1:144
	ds_read2_b32 v[138:139], v150 offset0:160 offset1:176
	s_movk_i32 s24, 0x2c00
	s_andn2_b64 vcc, exec, s[14:15]
	s_mov_b32 s49, 0x60000
	s_mov_b32 s52, 0x24000
	s_mov_b32 s53, 0x28000
	s_mov_b32 s58, 0x34000
	s_mov_b32 s59, 0x38000
	s_mov_b32 s60, 0x3c000
	s_mov_b32 s61, 0x44000
	s_mov_b32 s62, 0x48000
	s_mov_b32 s63, 0x4c000
	v_lshl_or_b32 v146, s0, 7, v151
	v_lshl_add_u32 v153, s1, 8, v148
	v_ashrrev_i32_e32 v147, 31, v146
	v_mov_b64_e32 v[154:155], s[10:11]
	v_lshlrev_b64 v[156:157], 1, v[146:147]
	v_mov_b32_e32 v166, 1.0
	s_waitcnt lgkmcnt(0)
	v_mul_f32_e32 v164, 0xbfb8aa3b, v144
	v_mul_f32_e32 v165, v144, v144
	v_pk_mul_f32 v[120:121], v[124:125], v[120:121]
	v_pk_mul_f32 v[122:123], v[126:127], v[122:123]
	v_pk_mul_f32 v[112:113], v[116:117], v[112:113]
	v_pk_mul_f32 v[114:115], v[118:119], v[114:115]
	v_pk_mul_f32 v[124:125], v[124:125], v[164:165] op_sel_hi:[1,0]
	v_pk_mul_f32 v[126:127], v[126:127], v[164:165] op_sel_hi:[1,0]
	v_pk_mul_f32 v[116:117], v[116:117], v[164:165] op_sel_hi:[1,0]
	v_pk_mul_f32 v[118:119], v[118:119], v[164:165] op_sel_hi:[1,0]
	v_exp_f32_e32 v124, v124
	v_exp_f32_e32 v125, v125
	v_exp_f32_e32 v126, v126
	v_exp_f32_e32 v127, v127
	v_exp_f32_e32 v116, v116
	v_exp_f32_e32 v117, v117
	v_exp_f32_e32 v118, v118
	v_exp_f32_e32 v119, v119
	v_pk_mul_f32 v[120:121], v[120:121], v[164:165] op_sel:[0,1] op_sel_hi:[1,1]
	v_pk_mul_f32 v[122:123], v[122:123], v[164:165] op_sel:[0,1] op_sel_hi:[1,1]
	v_pk_mul_f32 v[112:113], v[112:113], v[164:165] op_sel:[0,1] op_sel_hi:[1,1]
	v_pk_mul_f32 v[114:115], v[114:115], v[164:165] op_sel:[0,1] op_sel_hi:[1,1]
	v_pk_add_f32 v[124:125], v[124:125], v[166:167] op_sel_hi:[1,0]
	v_pk_add_f32 v[126:127], v[126:127], v[166:167] op_sel_hi:[1,0]
	v_pk_add_f32 v[116:117], v[116:117], v[166:167] op_sel_hi:[1,0]
	v_pk_add_f32 v[118:119], v[118:119], v[166:167] op_sel_hi:[1,0]
	v_rcp_f32_e32 v124, v124
	v_rcp_f32_e32 v125, v125
	v_rcp_f32_e32 v126, v126
	v_rcp_f32_e32 v127, v127
	v_rcp_f32_e32 v116, v116
	v_rcp_f32_e32 v117, v117
	v_rcp_f32_e32 v118, v118
	v_rcp_f32_e32 v119, v119
	v_mad_i64_i32 v[160:161], s[0:1], v153, s24, v[154:155]
	v_lshl_add_u64 v[160:161], v[160:161], 0, v[156:157]
	v_pk_mul_f32 v[120:121], v[120:121], v[124:125]
	v_pk_mul_f32 v[122:123], v[122:123], v[126:127]
	v_pk_mul_f32 v[112:113], v[112:113], v[116:117]
	v_pk_mul_f32 v[114:115], v[114:115], v[118:119]
	v_cvt_pk_bf16_f32 v124, v120, v121
	v_cvt_pk_bf16_f32 v125, v122, v123
	v_cvt_pk_bf16_f32 v126, v112, v113
	v_cvt_pk_bf16_f32 v127, v114, v115
	global_store_dwordx4 v[160:161], v[124:127], off sc0 sc1
	v_mul_f32_e32 v164, 0xbfb8aa3b, v145
	v_mul_f32_e32 v165, v145, v145
	v_pk_mul_f32 v[104:105], v[108:109], v[104:105]
	v_pk_mul_f32 v[106:107], v[110:111], v[106:107]
	v_pk_mul_f32 v[96:97], v[100:101], v[96:97]
	v_pk_mul_f32 v[98:99], v[102:103], v[98:99]
	v_pk_mul_f32 v[108:109], v[108:109], v[164:165] op_sel_hi:[1,0]
	v_pk_mul_f32 v[110:111], v[110:111], v[164:165] op_sel_hi:[1,0]
	v_pk_mul_f32 v[100:101], v[100:101], v[164:165] op_sel_hi:[1,0]
	v_pk_mul_f32 v[102:103], v[102:103], v[164:165] op_sel_hi:[1,0]
	v_exp_f32_e32 v108, v108
	v_exp_f32_e32 v109, v109
	v_exp_f32_e32 v110, v110
	v_exp_f32_e32 v111, v111
	v_exp_f32_e32 v100, v100
	v_exp_f32_e32 v101, v101
	v_exp_f32_e32 v102, v102
	v_exp_f32_e32 v103, v103
	v_pk_mul_f32 v[104:105], v[104:105], v[164:165] op_sel:[0,1] op_sel_hi:[1,1]
	v_pk_mul_f32 v[106:107], v[106:107], v[164:165] op_sel:[0,1] op_sel_hi:[1,1]
	v_pk_mul_f32 v[96:97], v[96:97], v[164:165] op_sel:[0,1] op_sel_hi:[1,1]
	v_pk_mul_f32 v[98:99], v[98:99], v[164:165] op_sel:[0,1] op_sel_hi:[1,1]
	v_pk_add_f32 v[108:109], v[108:109], v[166:167] op_sel_hi:[1,0]
	v_pk_add_f32 v[110:111], v[110:111], v[166:167] op_sel_hi:[1,0]
	v_pk_add_f32 v[100:101], v[100:101], v[166:167] op_sel_hi:[1,0]
	v_pk_add_f32 v[102:103], v[102:103], v[166:167] op_sel_hi:[1,0]
	v_rcp_f32_e32 v108, v108
	v_rcp_f32_e32 v109, v109
	v_rcp_f32_e32 v110, v110
	v_rcp_f32_e32 v111, v111
	v_rcp_f32_e32 v100, v100
	v_rcp_f32_e32 v101, v101
	v_rcp_f32_e32 v102, v102
	v_rcp_f32_e32 v103, v103
	v_add_u32_e32 v158, 0x10, v153
	v_mad_i64_i32 v[162:163], s[0:1], v158, s24, v[154:155]
	v_lshl_add_u64 v[162:163], v[162:163], 0, v[156:157]
	v_pk_mul_f32 v[104:105], v[104:105], v[108:109]
	v_pk_mul_f32 v[106:107], v[106:107], v[110:111]
	v_pk_mul_f32 v[96:97], v[96:97], v[100:101]
	v_pk_mul_f32 v[98:99], v[98:99], v[102:103]
	v_cvt_pk_bf16_f32 v108, v104, v105
	v_cvt_pk_bf16_f32 v109, v106, v107
	v_cvt_pk_bf16_f32 v110, v96, v97
	v_cvt_pk_bf16_f32 v111, v98, v99
	global_store_dwordx4 v[162:163], v[108:111], off sc0 sc1
	v_mul_f32_e32 v164, 0xbfb8aa3b, v142
	v_mul_f32_e32 v165, v142, v142
	v_pk_mul_f32 v[88:89], v[92:93], v[88:89]
	v_pk_mul_f32 v[90:91], v[94:95], v[90:91]
	v_pk_mul_f32 v[80:81], v[84:85], v[80:81]
	v_pk_mul_f32 v[82:83], v[86:87], v[82:83]
	v_pk_mul_f32 v[92:93], v[92:93], v[164:165] op_sel_hi:[1,0]
	v_pk_mul_f32 v[94:95], v[94:95], v[164:165] op_sel_hi:[1,0]
	v_pk_mul_f32 v[84:85], v[84:85], v[164:165] op_sel_hi:[1,0]
	v_pk_mul_f32 v[86:87], v[86:87], v[164:165] op_sel_hi:[1,0]
	v_exp_f32_e32 v92, v92
	v_exp_f32_e32 v93, v93
	v_exp_f32_e32 v94, v94
	v_exp_f32_e32 v95, v95
	v_exp_f32_e32 v84, v84
	v_exp_f32_e32 v85, v85
	v_exp_f32_e32 v86, v86
	v_exp_f32_e32 v87, v87
	v_pk_mul_f32 v[88:89], v[88:89], v[164:165] op_sel:[0,1] op_sel_hi:[1,1]
	v_pk_mul_f32 v[90:91], v[90:91], v[164:165] op_sel:[0,1] op_sel_hi:[1,1]
	v_pk_mul_f32 v[80:81], v[80:81], v[164:165] op_sel:[0,1] op_sel_hi:[1,1]
; __device__ __forceinline__ unsigned cvt_pk_bf16(float lo, float hi) { unsigned r; asm("v_cvt_pk_bf16_f32 %0, %1, %2" : "=v"(r) : "v"(lo), "v"(hi)); return r; }
;     __device__ __forceinline__ void operator()(const Acc& acc, const Unit& u, int wr, int wc, int fr, int fq) const {
;     ...
;         for (int ai = 0; ai < 2; ++ai)
; #pragma unroll
;             for (int m = 0; m < 4; ++m) {
;                 const int row = row0 + ai * HALF + m * 16;
;                 const float rr = rrv[ai * 4 + m];
;                 float r[8];
; #pragma unroll
;                 for (int n = 0; n < 2; ++n)
; #pragma unroll
;                     for (int j = 0; j < 4; ++j) {
;                         const float g = acc[ai][0][m][n][j] * rr, up = acc[ai][1][m][n][j] * rr;
;                         r[n * 4 + j] = g * __builtin_amdgcn_rcpf(1.f + __builtin_amdgcn_exp2f(-g * LOG2E)) * up;
;                     }
;                 u32x4 w; w.x = cvt_pk_bf16(r[0], r[1]); w.y = cvt_pk_bf16(r[2], r[3]); w.z = cvt_pk_bf16(r[4], r[5]); w.w = cvt_pk_bf16(r[6], r[7]);
;                 *(u32x4*)(O + (size_t)row * DFF + col0) = w;
;             }
	v_pk_mul_f32 v[82:83], v[82:83], v[164:165] op_sel:[0,1] op_sel_hi:[1,1]
	v_pk_add_f32 v[92:93], v[92:93], v[166:167] op_sel_hi:[1,0]
	v_pk_add_f32 v[94:95], v[94:95], v[166:167] op_sel_hi:[1,0]
	v_pk_add_f32 v[84:85], v[84:85], v[166:167] op_sel_hi:[1,0]
	v_pk_add_f32 v[86:87], v[86:87], v[166:167] op_sel_hi:[1,0]
	v_rcp_f32_e32 v92, v92
	v_rcp_f32_e32 v93, v93
	v_rcp_f32_e32 v94, v94
	v_rcp_f32_e32 v95, v95
	v_rcp_f32_e32 v84, v84
	v_rcp_f32_e32 v85, v85
	v_rcp_f32_e32 v86, v86
	v_rcp_f32_e32 v87, v87
	v_add_u32_e32 v158, 0x20, v153
	v_mad_i64_i32 v[160:161], s[0:1], v158, s24, v[154:155]
	v_lshl_add_u64 v[160:161], v[160:161], 0, v[156:157]
	v_pk_mul_f32 v[88:89], v[88:89], v[92:93]
	v_pk_mul_f32 v[90:91], v[90:91], v[94:95]
	v_pk_mul_f32 v[80:81], v[80:81], v[84:85]
	v_pk_mul_f32 v[82:83], v[82:83], v[86:87]
	v_cvt_pk_bf16_f32 v92, v88, v89
	v_cvt_pk_bf16_f32 v93, v90, v91
	v_cvt_pk_bf16_f32 v94, v80, v81
	v_cvt_pk_bf16_f32 v95, v82, v83
	global_store_dwordx4 v[160:161], v[92:95], off sc0 sc1
	v_mul_f32_e32 v164, 0xbfb8aa3b, v143
	v_mul_f32_e32 v165, v143, v143
	v_pk_mul_f32 v[72:73], v[76:77], v[72:73]
	v_pk_mul_f32 v[74:75], v[78:79], v[74:75]
	v_pk_mul_f32 v[64:65], v[68:69], v[64:65]
	v_pk_mul_f32 v[66:67], v[70:71], v[66:67]
	v_pk_mul_f32 v[76:77], v[76:77], v[164:165] op_sel_hi:[1,0]
	v_pk_mul_f32 v[78:79], v[78:79], v[164:165] op_sel_hi:[1,0]
	v_pk_mul_f32 v[68:69], v[68:69], v[164:165] op_sel_hi:[1,0]
	v_pk_mul_f32 v[70:71], v[70:71], v[164:165] op_sel_hi:[1,0]
	v_exp_f32_e32 v76, v76
	v_exp_f32_e32 v77, v77
	v_exp_f32_e32 v78, v78
	v_exp_f32_e32 v79, v79
	v_exp_f32_e32 v68, v68
	v_exp_f32_e32 v69, v69
	v_exp_f32_e32 v70, v70
	v_exp_f32_e32 v71, v71
	v_pk_mul_f32 v[72:73], v[72:73], v[164:165] op_sel:[0,1] op_sel_hi:[1,1]
	v_pk_mul_f32 v[74:75], v[74:75], v[164:165] op_sel:[0,1] op_sel_hi:[1,1]
	v_pk_mul_f32 v[64:65], v[64:65], v[164:165] op_sel:[0,1] op_sel_hi:[1,1]
	v_pk_mul_f32 v[66:67], v[66:67], v[164:165] op_sel:[0,1] op_sel_hi:[1,1]
	v_pk_add_f32 v[76:77], v[76:77], v[166:167] op_sel_hi:[1,0]
	v_pk_add_f32 v[78:79], v[78:79], v[166:167] op_sel_hi:[1,0]
	v_pk_add_f32 v[68:69], v[68:69], v[166:167] op_sel_hi:[1,0]
	v_pk_add_f32 v[70:71], v[70:71], v[166:167] op_sel_hi:[1,0]
	v_rcp_f32_e32 v76, v76
	v_rcp_f32_e32 v77, v77
	v_rcp_f32_e32 v78, v78
	v_rcp_f32_e32 v79, v79
	v_rcp_f32_e32 v68, v68
	v_rcp_f32_e32 v69, v69
	v_rcp_f32_e32 v70, v70
	v_rcp_f32_e32 v71, v71
	v_add_u32_e32 v158, 0x30, v153
	v_mad_i64_i32 v[162:163], s[0:1], v158, s24, v[154:155]
	v_lshl_add_u64 v[162:163], v[162:163], 0, v[156:157]
	v_pk_mul_f32 v[72:73], v[72:73], v[76:77]
	v_pk_mul_f32 v[74:75], v[74:75], v[78:79]
	v_pk_mul_f32 v[64:65], v[64:65], v[68:69]
	v_pk_mul_f32 v[66:67], v[66:67], v[70:71]
	v_cvt_pk_bf16_f32 v76, v72, v73
	v_cvt_pk_bf16_f32 v77, v74, v75
	v_cvt_pk_bf16_f32 v78, v64, v65
	v_cvt_pk_bf16_f32 v79, v66, v67
	global_store_dwordx4 v[162:163], v[76:79], off sc0 sc1
	v_mul_f32_e32 v164, 0xbfb8aa3b, v140
	v_mul_f32_e32 v165, v140, v140
	v_pk_mul_f32 v[56:57], v[60:61], v[56:57]
	v_pk_mul_f32 v[58:59], v[62:63], v[58:59]
	v_pk_mul_f32 v[48:49], v[52:53], v[48:49]
	v_pk_mul_f32 v[50:51], v[54:55], v[50:51]
	v_pk_mul_f32 v[60:61], v[60:61], v[164:165] op_sel_hi:[1,0]
	v_pk_mul_f32 v[62:63], v[62:63], v[164:165] op_sel_hi:[1,0]
	v_pk_mul_f32 v[52:53], v[52:53], v[164:165] op_sel_hi:[1,0]
	v_pk_mul_f32 v[54:55], v[54:55], v[164:165] op_sel_hi:[1,0]
	v_exp_f32_e32 v60, v60
	v_exp_f32_e32 v61, v61
	v_exp_f32_e32 v62, v62
	v_exp_f32_e32 v63, v63
	v_exp_f32_e32 v52, v52
	v_exp_f32_e32 v53, v53
	v_exp_f32_e32 v54, v54
	v_exp_f32_e32 v55, v55
	v_pk_mul_f32 v[56:57], v[56:57], v[164:165] op_sel:[0,1] op_sel_hi:[1,1]
	v_pk_mul_f32 v[58:59], v[58:59], v[164:165] op_sel:[0,1] op_sel_hi:[1,1]
	v_pk_mul_f32 v[48:49], v[48:49], v[164:165] op_sel:[0,1] op_sel_hi:[1,1]
	v_pk_mul_f32 v[50:51], v[50:51], v[164:165] op_sel:[0,1] op_sel_hi:[1,1]
	v_pk_add_f32 v[60:61], v[60:61], v[166:167] op_sel_hi:[1,0]
	v_pk_add_f32 v[62:63], v[62:63], v[166:167] op_sel_hi:[1,0]
	v_pk_add_f32 v[52:53], v[52:53], v[166:167] op_sel_hi:[1,0]
	v_pk_add_f32 v[54:55], v[54:55], v[166:167] op_sel_hi:[1,0]
	v_rcp_f32_e32 v60, v60
	v_rcp_f32_e32 v61, v61
	v_rcp_f32_e32 v62, v62
	v_rcp_f32_e32 v63, v63
	v_rcp_f32_e32 v52, v52
	v_rcp_f32_e32 v53, v53
	v_rcp_f32_e32 v54, v54
	v_rcp_f32_e32 v55, v55
	v_add_u32_e32 v158, 0x80, v153
	v_mad_i64_i32 v[160:161], s[0:1], v158, s24, v[154:155]
	v_lshl_add_u64 v[160:161], v[160:161], 0, v[156:157]
	v_pk_mul_f32 v[56:57], v[56:57], v[60:61]
	v_pk_mul_f32 v[58:59], v[58:59], v[62:63]
	v_pk_mul_f32 v[48:49], v[48:49], v[52:53]
	v_pk_mul_f32 v[50:51], v[50:51], v[54:55]
	v_cvt_pk_bf16_f32 v60, v56, v57
	v_cvt_pk_bf16_f32 v61, v58, v59
	v_cvt_pk_bf16_f32 v62, v48, v49
	v_cvt_pk_bf16_f32 v63, v50, v51
	global_store_dwordx4 v[160:161], v[60:63], off sc0 sc1
	v_mul_f32_e32 v164, 0xbfb8aa3b, v141
	v_mul_f32_e32 v165, v141, v141
	v_pk_mul_f32 v[40:41], v[44:45], v[40:41]
	v_pk_mul_f32 v[42:43], v[46:47], v[42:43]
	v_pk_mul_f32 v[32:33], v[36:37], v[32:33]
	v_pk_mul_f32 v[34:35], v[38:39], v[34:35]
	v_pk_mul_f32 v[44:45], v[44:45], v[164:165] op_sel_hi:[1,0]
	v_pk_mul_f32 v[46:47], v[46:47], v[164:165] op_sel_hi:[1,0]
	v_pk_mul_f32 v[36:37], v[36:37], v[164:165] op_sel_hi:[1,0]
	v_pk_mul_f32 v[38:39], v[38:39], v[164:165] op_sel_hi:[1,0]
; __device__ __forceinline__ unsigned cvt_pk_bf16(float lo, float hi) { unsigned r; asm("v_cvt_pk_bf16_f32 %0, %1, %2" : "=v"(r) : "v"(lo), "v"(hi)); return r; }
;     __device__ __forceinline__ void operator()(const Acc& acc, const Unit& u, int wr, int wc, int fr, int fq) const {
;     ...
;         for (int ai = 0; ai < 2; ++ai)
; #pragma unroll
;             for (int m = 0; m < 4; ++m) {
;                 const int row = row0 + ai * HALF + m * 16;
;                 const float rr = rrv[ai * 4 + m];
;                 float r[8];
; #pragma unroll
;                 for (int n = 0; n < 2; ++n)
; #pragma unroll
;                     for (int j = 0; j < 4; ++j) {
;                         const float g = acc[ai][0][m][n][j] * rr, up = acc[ai][1][m][n][j] * rr;
;                         r[n * 4 + j] = g * __builtin_amdgcn_rcpf(1.f + __builtin_amdgcn_exp2f(-g * LOG2E)) * up;
;                     }
;                 u32x4 w; w.x = cvt_pk_bf16(r[0], r[1]); w.y = cvt_pk_bf16(r[2], r[3]); w.z = cvt_pk_bf16(r[4], r[5]); w.w = cvt_pk_bf16(r[6], r[7]);
;                 *(u32x4*)(O + (size_t)row * DFF + col0) = w;
;             }
	v_exp_f32_e32 v44, v44
	v_exp_f32_e32 v45, v45
	v_exp_f32_e32 v46, v46
	v_exp_f32_e32 v47, v47
	v_exp_f32_e32 v36, v36
	v_exp_f32_e32 v37, v37
	v_exp_f32_e32 v38, v38
	v_exp_f32_e32 v39, v39
	v_pk_mul_f32 v[40:41], v[40:41], v[164:165] op_sel:[0,1] op_sel_hi:[1,1]
	v_pk_mul_f32 v[42:43], v[42:43], v[164:165] op_sel:[0,1] op_sel_hi:[1,1]
	v_pk_mul_f32 v[32:33], v[32:33], v[164:165] op_sel:[0,1] op_sel_hi:[1,1]
	v_pk_mul_f32 v[34:35], v[34:35], v[164:165] op_sel:[0,1] op_sel_hi:[1,1]
	v_pk_add_f32 v[44:45], v[44:45], v[166:167] op_sel_hi:[1,0]
	v_pk_add_f32 v[46:47], v[46:47], v[166:167] op_sel_hi:[1,0]
	v_pk_add_f32 v[36:37], v[36:37], v[166:167] op_sel_hi:[1,0]
	v_pk_add_f32 v[38:39], v[38:39], v[166:167] op_sel_hi:[1,0]
	v_rcp_f32_e32 v44, v44
	v_rcp_f32_e32 v45, v45
	v_rcp_f32_e32 v46, v46
	v_rcp_f32_e32 v47, v47
	v_rcp_f32_e32 v36, v36
	v_rcp_f32_e32 v37, v37
	v_rcp_f32_e32 v38, v38
	v_rcp_f32_e32 v39, v39
	v_add_u32_e32 v158, 0x90, v153
	v_mad_i64_i32 v[162:163], s[0:1], v158, s24, v[154:155]
	v_lshl_add_u64 v[162:163], v[162:163], 0, v[156:157]
	v_pk_mul_f32 v[40:41], v[40:41], v[44:45]
	v_pk_mul_f32 v[42:43], v[42:43], v[46:47]
	v_pk_mul_f32 v[32:33], v[32:33], v[36:37]
	v_pk_mul_f32 v[34:35], v[34:35], v[38:39]
	v_cvt_pk_bf16_f32 v44, v40, v41
	v_cvt_pk_bf16_f32 v45, v42, v43
	v_cvt_pk_bf16_f32 v46, v32, v33
	v_cvt_pk_bf16_f32 v47, v34, v35
	global_store_dwordx4 v[162:163], v[44:47], off sc0 sc1
	v_mul_f32_e32 v164, 0xbfb8aa3b, v138
	v_mul_f32_e32 v165, v138, v138
	v_pk_mul_f32 v[24:25], v[28:29], v[24:25]
	v_pk_mul_f32 v[26:27], v[30:31], v[26:27]
	v_pk_mul_f32 v[16:17], v[20:21], v[16:17]
	v_pk_mul_f32 v[18:19], v[22:23], v[18:19]
	v_pk_mul_f32 v[28:29], v[28:29], v[164:165] op_sel_hi:[1,0]
	v_pk_mul_f32 v[30:31], v[30:31], v[164:165] op_sel_hi:[1,0]
	v_pk_mul_f32 v[20:21], v[20:21], v[164:165] op_sel_hi:[1,0]
	v_pk_mul_f32 v[22:23], v[22:23], v[164:165] op_sel_hi:[1,0]
	v_exp_f32_e32 v28, v28
	v_exp_f32_e32 v29, v29
	v_exp_f32_e32 v30, v30
	v_exp_f32_e32 v31, v31
	v_exp_f32_e32 v20, v20
	v_exp_f32_e32 v21, v21
	v_exp_f32_e32 v22, v22
	v_exp_f32_e32 v23, v23
	v_pk_mul_f32 v[24:25], v[24:25], v[164:165] op_sel:[0,1] op_sel_hi:[1,1]
	v_pk_mul_f32 v[26:27], v[26:27], v[164:165] op_sel:[0,1] op_sel_hi:[1,1]
	v_pk_mul_f32 v[16:17], v[16:17], v[164:165] op_sel:[0,1] op_sel_hi:[1,1]
	v_pk_mul_f32 v[18:19], v[18:19], v[164:165] op_sel:[0,1] op_sel_hi:[1,1]
	v_pk_add_f32 v[28:29], v[28:29], v[166:167] op_sel_hi:[1,0]
	v_pk_add_f32 v[30:31], v[30:31], v[166:167] op_sel_hi:[1,0]
	v_pk_add_f32 v[20:21], v[20:21], v[166:167] op_sel_hi:[1,0]
	v_pk_add_f32 v[22:23], v[22:23], v[166:167] op_sel_hi:[1,0]
	v_rcp_f32_e32 v28, v28
	v_rcp_f32_e32 v29, v29
	v_rcp_f32_e32 v30, v30
	v_rcp_f32_e32 v31, v31
	v_rcp_f32_e32 v20, v20
	v_rcp_f32_e32 v21, v21
	v_rcp_f32_e32 v22, v22
	v_rcp_f32_e32 v23, v23
	v_add_u32_e32 v158, 0xa0, v153
	v_mad_i64_i32 v[160:161], s[0:1], v158, s24, v[154:155]
	v_lshl_add_u64 v[160:161], v[160:161], 0, v[156:157]
	v_pk_mul_f32 v[24:25], v[24:25], v[28:29]
	v_pk_mul_f32 v[26:27], v[26:27], v[30:31]
	v_pk_mul_f32 v[16:17], v[16:17], v[20:21]
	v_pk_mul_f32 v[18:19], v[18:19], v[22:23]
	v_cvt_pk_bf16_f32 v28, v24, v25
	v_cvt_pk_bf16_f32 v29, v26, v27
	v_cvt_pk_bf16_f32 v30, v16, v17
	v_cvt_pk_bf16_f32 v31, v18, v19
	global_store_dwordx4 v[160:161], v[28:31], off sc0 sc1
	v_mul_f32_e32 v164, 0xbfb8aa3b, v139
	v_mul_f32_e32 v165, v139, v139
	v_pk_mul_f32 v[8:9], v[12:13], v[8:9]
	v_pk_mul_f32 v[10:11], v[14:15], v[10:11]
	v_pk_mul_f32 v[0:1], v[4:5], v[0:1]
	v_pk_mul_f32 v[2:3], v[6:7], v[2:3]
	v_pk_mul_f32 v[12:13], v[12:13], v[164:165] op_sel_hi:[1,0]
	v_pk_mul_f32 v[14:15], v[14:15], v[164:165] op_sel_hi:[1,0]
	v_pk_mul_f32 v[4:5], v[4:5], v[164:165] op_sel_hi:[1,0]
	v_pk_mul_f32 v[6:7], v[6:7], v[164:165] op_sel_hi:[1,0]
	v_exp_f32_e32 v12, v12
	v_exp_f32_e32 v13, v13
	v_exp_f32_e32 v14, v14
	v_exp_f32_e32 v15, v15
	v_exp_f32_e32 v4, v4
	v_exp_f32_e32 v5, v5
	v_exp_f32_e32 v6, v6
	v_exp_f32_e32 v7, v7
	v_pk_mul_f32 v[8:9], v[8:9], v[164:165] op_sel:[0,1] op_sel_hi:[1,1]
	v_pk_mul_f32 v[10:11], v[10:11], v[164:165] op_sel:[0,1] op_sel_hi:[1,1]
	v_pk_mul_f32 v[0:1], v[0:1], v[164:165] op_sel:[0,1] op_sel_hi:[1,1]
	v_pk_mul_f32 v[2:3], v[2:3], v[164:165] op_sel:[0,1] op_sel_hi:[1,1]
	v_pk_add_f32 v[12:13], v[12:13], v[166:167] op_sel_hi:[1,0]
	v_pk_add_f32 v[14:15], v[14:15], v[166:167] op_sel_hi:[1,0]
	v_pk_add_f32 v[4:5], v[4:5], v[166:167] op_sel_hi:[1,0]
	v_pk_add_f32 v[6:7], v[6:7], v[166:167] op_sel_hi:[1,0]
	v_rcp_f32_e32 v12, v12
	v_rcp_f32_e32 v13, v13
	v_rcp_f32_e32 v14, v14
	v_rcp_f32_e32 v15, v15
	v_rcp_f32_e32 v4, v4
	v_rcp_f32_e32 v5, v5
	v_rcp_f32_e32 v6, v6
	v_rcp_f32_e32 v7, v7
	v_add_u32_e32 v158, 0xb0, v153
	v_mad_i64_i32 v[162:163], s[0:1], v158, s24, v[154:155]
	v_lshl_add_u64 v[162:163], v[162:163], 0, v[156:157]
	v_pk_mul_f32 v[8:9], v[8:9], v[12:13]
	v_pk_mul_f32 v[10:11], v[10:11], v[14:15]
	v_pk_mul_f32 v[0:1], v[0:1], v[4:5]
	v_pk_mul_f32 v[2:3], v[2:3], v[6:7]
	v_cvt_pk_bf16_f32 v12, v8, v9
	v_cvt_pk_bf16_f32 v13, v10, v11
	v_cvt_pk_bf16_f32 v14, v0, v1
	v_cvt_pk_bf16_f32 v15, v2, v3
	s_mov_b64 s[0:1], -1
	global_store_dwordx4 v[162:163], v[12:15], off sc0 sc1
	s_cbranch_vccnz .LBB0_679
	s_andn2_b64 vcc, exec, s[8:9]
	s_cbranch_vccnz .LBB0_678
	s_barrier
	s_branch .LBB0_678

; __device__ __forceinline__ unsigned cvt_pk_bf16(float lo, float hi) { unsigned r; asm("v_cvt_pk_bf16_f32 %0, %1, %2" : "=v"(r) : "v"(lo), "v"(hi)); return r; }
;     __device__ __forceinline__ void operator()(const Acc& acc, const Unit& u, int wr, int wc, int fr, int fq) const {
;     ...
;         for (int ai = 0; ai < 2; ++ai)
; #pragma unroll
;             for (int m = 0; m < 4; ++m) {
;                 const int row = row0 + ai * HALF + m * 16;
;                 const float rr = ssq ? rms_r(rrv[ai * 4 + m]) : 1.f;
;                 bf16_t* rowp = O + (size_t)row * ldc + col0;
; #pragma unroll
;                 for (int bj = 0; bj < 2; ++bj) {
;                     const f32x4 v0 = acc[ai][bj][m][0] * rr + bv[bj][0], v1 = acc[ai][bj][m][1] * rr + bv[bj][1];
;                     u32x4 w; w.x = cvt_pk_bf16(v0[0], v0[1]); w.y = cvt_pk_bf16(v0[2], v0[3]); w.z = cvt_pk_bf16(v1[0], v1[1]); w.w = cvt_pk_bf16(v1[2], v1[3]);
;                     *(u32x4*)(rowp + bj * HALF) = w;
.LBB0_696:
	v_lshl_add_u32 v140, s0, 8, v136
	v_lshl_or_b32 v134, s1, 8, v138
	v_ashrrev_i32_e32 v141, 31, v140
	v_ashrrev_i32_e32 v135, 31, v134
	v_lshlrev_b64 v[142:143], 12, v[140:141]
	v_lshl_add_u64 v[142:143], s[8:9], 0, v[142:143]
	v_lshlrev_b64 v[144:145], 1, v[134:135]
	v_lshl_add_u64 v[134:135], v[142:143], 0, v[144:145]
	v_pk_add_f32 v[126:127], v[126:127], 0 op_sel_hi:[1,0]
	v_pk_add_f32 v[124:125], v[124:125], 0 op_sel_hi:[1,0]
	v_pk_add_f32 v[142:143], v[122:123], 0 op_sel_hi:[1,0]
	v_pk_add_f32 v[122:123], v[120:121], 0 op_sel_hi:[1,0]
	v_cvt_pk_bf16_f32 v120, v124, v125
	v_cvt_pk_bf16_f32 v121, v126, v127
	v_pk_add_f32 v[116:117], v[116:117], 0 op_sel_hi:[1,0]
	v_cvt_pk_bf16_f32 v122, v122, v123
	v_cvt_pk_bf16_f32 v123, v142, v143
	global_store_dwordx4 v[134:135], v[120:123], off sc0 sc1
	v_pk_add_f32 v[118:119], v[118:119], 0 op_sel_hi:[1,0]
	v_pk_add_f32 v[110:111], v[110:111], 0 op_sel_hi:[1,0]
	v_pk_add_f32 v[120:121], v[114:115], 0 op_sel_hi:[1,0]
	v_pk_add_f32 v[114:115], v[112:113], 0 op_sel_hi:[1,0]
	v_cvt_pk_bf16_f32 v112, v116, v117
	v_cvt_pk_bf16_f32 v113, v118, v119
	v_pk_add_f32 v[108:109], v[108:109], 0 op_sel_hi:[1,0]
	v_cvt_pk_bf16_f32 v114, v114, v115
	v_cvt_pk_bf16_f32 v115, v120, v121
	global_store_dwordx4 v[134:135], v[112:115], off offset:256 sc0 sc1
	v_pk_add_f32 v[100:101], v[100:101], 0 op_sel_hi:[1,0]
	v_pk_add_f32 v[102:103], v[102:103], 0 op_sel_hi:[1,0]
	v_or_b32_e32 v112, 16, v140
	v_ashrrev_i32_e32 v113, 31, v112
	v_lshlrev_b64 v[112:113], 12, v[112:113]
	v_lshl_add_u64 v[112:113], s[8:9], 0, v[112:113]
	v_lshl_add_u64 v[112:113], v[112:113], 0, v[144:145]
	v_pk_add_f32 v[114:115], v[106:107], 0 op_sel_hi:[1,0]
	v_pk_add_f32 v[106:107], v[104:105], 0 op_sel_hi:[1,0]
	v_cvt_pk_bf16_f32 v104, v108, v109
	v_cvt_pk_bf16_f32 v105, v110, v111
	v_pk_add_f32 v[94:95], v[94:95], 0 op_sel_hi:[1,0]
	v_cvt_pk_bf16_f32 v106, v106, v107
	v_cvt_pk_bf16_f32 v107, v114, v115
	global_store_dwordx4 v[112:113], v[104:107], off sc0 sc1
	v_pk_add_f32 v[92:93], v[92:93], 0 op_sel_hi:[1,0]
	v_pk_add_f32 v[84:85], v[84:85], 0 op_sel_hi:[1,0]
	v_pk_add_f32 v[104:105], v[98:99], 0 op_sel_hi:[1,0]
	v_pk_add_f32 v[98:99], v[96:97], 0 op_sel_hi:[1,0]
	v_cvt_pk_bf16_f32 v96, v100, v101
	v_cvt_pk_bf16_f32 v97, v102, v103
	v_pk_add_f32 v[86:87], v[86:87], 0 op_sel_hi:[1,0]
	v_cvt_pk_bf16_f32 v98, v98, v99
	v_cvt_pk_bf16_f32 v99, v104, v105
	global_store_dwordx4 v[112:113], v[96:99], off offset:256 sc0 sc1
	v_pk_add_f32 v[70:71], v[70:71], 0 op_sel_hi:[1,0]
	v_pk_add_f32 v[68:69], v[68:69], 0 op_sel_hi:[1,0]
	v_or_b32_e32 v96, 32, v140
	v_ashrrev_i32_e32 v97, 31, v96
	v_lshlrev_b64 v[96:97], 12, v[96:97]
	v_lshl_add_u64 v[96:97], s[8:9], 0, v[96:97]
	v_lshl_add_u64 v[96:97], v[96:97], 0, v[144:145]
	v_pk_add_f32 v[98:99], v[90:91], 0 op_sel_hi:[1,0]
	v_pk_add_f32 v[90:91], v[88:89], 0 op_sel_hi:[1,0]
	v_cvt_pk_bf16_f32 v88, v92, v93
	v_cvt_pk_bf16_f32 v89, v94, v95
	v_pk_add_f32 v[54:55], v[54:55], 0 op_sel_hi:[1,0]
	v_cvt_pk_bf16_f32 v90, v90, v91
	v_cvt_pk_bf16_f32 v91, v98, v99
	global_store_dwordx4 v[96:97], v[88:91], off sc0 sc1
	v_pk_add_f32 v[52:53], v[52:53], 0 op_sel_hi:[1,0]
	s_mov_b64 s[0:1], 0x80000
	v_pk_add_f32 v[88:89], v[82:83], 0 op_sel_hi:[1,0]
	v_pk_add_f32 v[82:83], v[80:81], 0 op_sel_hi:[1,0]
	v_cvt_pk_bf16_f32 v80, v84, v85
	v_cvt_pk_bf16_f32 v81, v86, v87
	v_pk_add_f32 v[56:57], v[56:57], 0 op_sel_hi:[1,0]
	v_cvt_pk_bf16_f32 v82, v82, v83
	v_cvt_pk_bf16_f32 v83, v88, v89
	global_store_dwordx4 v[96:97], v[80:83], off offset:256 sc0 sc1
	v_pk_add_f32 v[44:45], v[44:45], 0 op_sel_hi:[1,0]
	v_pk_add_f32 v[46:47], v[46:47], 0 op_sel_hi:[1,0]
	v_or_b32_e32 v80, 48, v140
	v_ashrrev_i32_e32 v81, 31, v80
	v_lshlrev_b64 v[80:81], 12, v[80:81]
	v_lshl_add_u64 v[80:81], s[8:9], 0, v[80:81]
	v_lshl_add_u64 v[80:81], v[80:81], 0, v[144:145]
	v_pk_add_f32 v[82:83], v[66:67], 0 op_sel_hi:[1,0]
	v_pk_add_f32 v[66:67], v[64:65], 0 op_sel_hi:[1,0]
	v_cvt_pk_bf16_f32 v64, v68, v69
	v_cvt_pk_bf16_f32 v65, v70, v71
	v_pk_add_f32 v[28:29], v[28:29], 0 op_sel_hi:[1,0]
	v_cvt_pk_bf16_f32 v66, v66, v67
	v_cvt_pk_bf16_f32 v67, v82, v83
	global_store_dwordx4 v[80:81], v[64:67], off sc0 sc1
	v_pk_add_f32 v[38:39], v[38:39], 0 op_sel_hi:[1,0]
; __device__ __forceinline__ unsigned cvt_pk_bf16(float lo, float hi) { unsigned r; asm("v_cvt_pk_bf16_f32 %0, %1, %2" : "=v"(r) : "v"(lo), "v"(hi)); return r; }
;     __device__ __forceinline__ void operator()(const Acc& acc, const Unit& u, int wr, int wc, int fr, int fq) const {
;     ...
;         for (int ai = 0; ai < 2; ++ai)
; #pragma unroll
;             for (int m = 0; m < 4; ++m) {
;                 const int row = row0 + ai * HALF + m * 16;
;                 const float rr = ssq ? rms_r(rrv[ai * 4 + m]) : 1.f;
;                 bf16_t* rowp = O + (size_t)row * ldc + col0;
; #pragma unroll
;                 for (int bj = 0; bj < 2; ++bj) {
;                     const f32x4 v0 = acc[ai][bj][m][0] * rr + bv[bj][0], v1 = acc[ai][bj][m][1] * rr + bv[bj][1];
;                     u32x4 w; w.x = cvt_pk_bf16(v0[0], v0[1]); w.y = cvt_pk_bf16(v0[2], v0[3]); w.z = cvt_pk_bf16(v1[0], v1[1]); w.w = cvt_pk_bf16(v1[2], v1[3]);
;                     *(u32x4*)(rowp + bj * HALF) = w;
	v_pk_add_f32 v[36:37], v[36:37], 0 op_sel_hi:[1,0]
	v_pk_add_f32 v[64:65], v[50:51], 0 op_sel_hi:[1,0]
	v_pk_add_f32 v[50:51], v[48:49], 0 op_sel_hi:[1,0]
	v_cvt_pk_bf16_f32 v48, v52, v53
	v_cvt_pk_bf16_f32 v49, v54, v55
	v_pk_add_f32 v[54:55], v[74:75], 0 op_sel_hi:[1,0]
	v_cvt_pk_bf16_f32 v50, v50, v51
	v_cvt_pk_bf16_f32 v51, v64, v65
	global_store_dwordx4 v[80:81], v[48:51], off offset:256 sc0 sc1
	v_pk_add_f32 v[64:65], v[72:73], 0 op_sel_hi:[1,0]
	v_lshl_add_u64 v[52:53], v[134:135], 0, s[0:1]
	v_pk_add_f32 v[50:51], v[78:79], 0 op_sel_hi:[1,0]
	v_pk_add_f32 v[48:49], v[76:77], 0 op_sel_hi:[1,0]
	s_mov_b64 s[0:1], 0x90000
	v_cvt_pk_bf16_f32 v48, v48, v49
	v_cvt_pk_bf16_f32 v49, v50, v51
	v_cvt_pk_bf16_f32 v51, v54, v55
	v_add_co_u32_e32 v54, vcc, s77, v134
	v_cvt_pk_bf16_f32 v50, v64, v65
	v_pk_add_f32 v[30:31], v[30:31], 0 op_sel_hi:[1,0]
	s_nop 0
	v_addc_co_u32_e32 v55, vcc, 0, v135, vcc
	global_store_dwordx4 v[54:55], v[48:51], off sc0 sc1
	v_pk_add_f32 v[54:55], v[58:59], 0 op_sel_hi:[1,0]
	v_pk_add_f32 v[12:13], v[12:13], 0 op_sel_hi:[1,0]
	v_pk_add_f32 v[50:51], v[62:63], 0 op_sel_hi:[1,0]
	v_pk_add_f32 v[48:49], v[60:61], 0 op_sel_hi:[1,0]
	s_mov_b32 s68, 0xb0000
	v_cvt_pk_bf16_f32 v48, v48, v49
	v_cvt_pk_bf16_f32 v49, v50, v51
	v_cvt_pk_bf16_f32 v50, v56, v57
	v_cvt_pk_bf16_f32 v51, v54, v55
	global_store_dwordx4 v[52:53], v[48:51], off offset:256 sc0 sc1
	v_pk_add_f32 v[22:23], v[22:23], 0 op_sel_hi:[1,0]
	v_pk_add_f32 v[20:21], v[20:21], 0 op_sel_hi:[1,0]
	v_pk_add_f32 v[50:51], v[42:43], 0 op_sel_hi:[1,0]
	v_pk_add_f32 v[42:43], v[40:41], 0 op_sel_hi:[1,0]
	v_cvt_pk_bf16_f32 v40, v44, v45
	v_add_co_u32_e32 v44, vcc, s76, v134
	v_cvt_pk_bf16_f32 v41, v46, v47
	v_cvt_pk_bf16_f32 v42, v42, v43
	v_cvt_pk_bf16_f32 v43, v50, v51
	v_lshl_add_u64 v[48:49], v[134:135], 0, s[0:1]
	s_nop 0
	v_addc_co_u32_e32 v45, vcc, 0, v135, vcc
	global_store_dwordx4 v[44:45], v[40:43], off sc0 sc1
	s_mov_b64 s[0:1], 0xa0000
	v_pk_add_f32 v[14:15], v[14:15], 0 op_sel_hi:[1,0]
	v_pk_add_f32 v[40:41], v[34:35], 0 op_sel_hi:[1,0]
	v_pk_add_f32 v[34:35], v[32:33], 0 op_sel_hi:[1,0]
	v_cvt_pk_bf16_f32 v32, v36, v37
	v_cvt_pk_bf16_f32 v33, v38, v39
	s_mov_b32 s52, 0x24000
	v_cvt_pk_bf16_f32 v34, v34, v35
	v_cvt_pk_bf16_f32 v35, v40, v41
	global_store_dwordx4 v[48:49], v[32:35], off offset:256 sc0 sc1
	s_mov_b32 s53, 0x28000
	s_mov_b32 s58, 0x34000
	v_pk_add_f32 v[34:35], v[26:27], 0 op_sel_hi:[1,0]
	v_pk_add_f32 v[26:27], v[24:25], 0 op_sel_hi:[1,0]
	v_cvt_pk_bf16_f32 v24, v28, v29
	v_add_co_u32_e32 v28, vcc, s56, v134
	v_cvt_pk_bf16_f32 v25, v30, v31
	v_cvt_pk_bf16_f32 v26, v26, v27
	v_cvt_pk_bf16_f32 v27, v34, v35
	v_lshl_add_u64 v[32:33], v[134:135], 0, s[0:1]
	s_nop 0
	v_addc_co_u32_e32 v29, vcc, 0, v135, vcc
	global_store_dwordx4 v[28:29], v[24:27], off sc0 sc1
	s_mov_b64 s[0:1], 0xb0000
	s_mov_b32 s59, 0x38000
	v_pk_add_f32 v[24:25], v[18:19], 0 op_sel_hi:[1,0]
	v_pk_add_f32 v[18:19], v[16:17], 0 op_sel_hi:[1,0]
	v_cvt_pk_bf16_f32 v16, v20, v21
	v_cvt_pk_bf16_f32 v17, v22, v23
	s_mov_b32 s60, 0x3c000
	v_cvt_pk_bf16_f32 v18, v18, v19
	v_cvt_pk_bf16_f32 v19, v24, v25
	global_store_dwordx4 v[32:33], v[16:19], off offset:256 sc0 sc1
	s_mov_b32 s61, 0x44000
	s_mov_b32 s62, 0x48000
	v_pk_add_f32 v[18:19], v[10:11], 0 op_sel_hi:[1,0]
	v_pk_add_f32 v[10:11], v[8:9], 0 op_sel_hi:[1,0]
	v_cvt_pk_bf16_f32 v8, v12, v13
	v_add_co_u32_e32 v12, vcc, s68, v134
	v_cvt_pk_bf16_f32 v9, v14, v15
	v_lshl_add_u64 v[16:17], v[134:135], 0, s[0:1]
	s_nop 0
	v_addc_co_u32_e32 v13, vcc, 0, v135, vcc
	v_cvt_pk_bf16_f32 v10, v10, v11
	v_cvt_pk_bf16_f32 v11, v18, v19
	global_store_dwordx4 v[12:13], v[8:11], off sc0 sc1
	s_andn2_b64 vcc, exec, s[14:15]
	s_mov_b64 s[0:1], -1
	v_pk_add_f32 v[8:9], v[2:3], 0 op_sel_hi:[1,0]
	v_pk_add_f32 v[2:3], v[0:1], 0 op_sel_hi:[1,0]
	s_mov_b32 s63, 0x4c000
	v_pk_add_f32 v[6:7], v[6:7], 0 op_sel_hi:[1,0]
	v_pk_add_f32 v[4:5], v[4:5], 0 op_sel_hi:[1,0]
	v_cvt_pk_bf16_f32 v1, v6, v7
	v_cvt_pk_bf16_f32 v2, v2, v3
	v_cvt_pk_bf16_f32 v3, v8, v9
	s_nop 0
	v_cvt_pk_bf16_f32 v0, v4, v5
	global_store_dwordx4 v[16:17], v[0:3], off offset:256 sc0 sc1
	s_cbranch_vccnz .LBB0_693
	s_andn2_b64 vcc, exec, s[6:7]
	s_cbranch_vccnz .LBB0_692
	s_barrier
	s_branch .LBB0_692

; __device__ __forceinline__ int tid_now(int wave_s) { int l; asm volatile("v_mbcnt_lo_u32_b32 %0, -1, 0\n\tv_mbcnt_hi_u32_b32 %0, -1, %0" : "=v"(l)); return wave_s * 64 + l; }
;     __device__ __forceinline__ void operator()(pg8::Acc& acc, const pg8::Unit& u, int wr, int wc, int fr, int fq) const {
;     ...
;         xcd_barrier(bar, tid_now(wave_s) == 0);
;         const int row0 = u.pm * pg8::BM + wr * 64 + fr, col0 = u.pn * pg8::BM + wc * 32 + 8 * fq;
;         f32x4 gv[2][2];
; #pragma unroll
;         for (int bj = 0; bj < 2; ++bj)
; #pragma unroll
;             for (int n = 0; n < 2; ++n) gv[bj][n] = *(const f32x4*)(gfin + col0 + bj * pg8::HALF + 4 * n);
;         pg8::ssq_t sv[8];
; #pragma unroll
;         for (int q = 0; q < 8; ++q) sv[q] = base.ssq_out[row0 + (q >> 2) * pg8::HALF + (q & 3) * 16];
; #pragma unroll
;         for (int ai = 0; ai < 2; ++ai)
; #pragma unroll
;             for (int m = 0; m < 4; ++m) {
;                 const float rr = pg8::rms_r(sv[ai * 4 + m]);
;                 float* op = out + (size_t)(row0 + ai * pg8::HALF + m * 16) * D + col0;
; #pragma unroll
;                 for (int bj = 0; bj < 2; ++bj) {
;                     *(f32x4*)(op + bj * pg8::HALF) = acc[ai][bj][m][0] * rr * gv[bj][0];
;                     *(f32x4*)(op + bj * pg8::HALF + 4) = acc[ai][bj][m][1] * rr * gv[bj][1];
;                 }
.LBB0_1050:
	s_or_b64 exec, exec, s[38:39]
	v_lshlrev_b64 v[38:39], 2, v[190:191]
	v_lshl_add_u64 v[4:5], s[44:45], 0, v[38:39]
	s_waitcnt lgkmcnt(0)
	s_barrier
	global_load_dwordx4 v[8:11], v[4:5], off offset:16
	global_load_dwordx4 v[12:15], v[4:5], off
	global_load_dwordx4 v[0:3], v[4:5], off offset:528
	s_nop 0
	global_load_dwordx4 v[4:7], v[4:5], off offset:512
	s_nop 0
	global_load_dword v58, v[36:37], off
	global_load_dword v63, v[36:37], off offset:64
	global_load_dword v52, v[36:37], off offset:128
	global_load_dword v57, v[36:37], off offset:192
	global_load_dword v56, v[36:37], off offset:512
	global_load_dword v55, v[36:37], off offset:576
	global_load_dword v54, v[36:37], off offset:640
	global_load_dword v53, v[36:37], off offset:704
	v_mov_b32_e32 v36, 0x358637bd
	s_waitcnt vmcnt(7)
	v_cvt_f32_u32_e32 v37, v58
	s_waitcnt vmcnt(5)
	v_cvt_f32_u32_e32 v52, v52
	s_waitcnt vmcnt(4)
	v_cvt_f32_u32_e32 v57, v57
	v_fmac_f32_e32 v36, 0x36800000, v37
	v_cmp_gt_f32_e32 vcc, s66, v36
	v_mul_f32_e32 v37, 0x4f800000, v36
	s_nop 0
	v_cndmask_b32_e32 v36, v36, v37, vcc
	v_sqrt_f32_e32 v37, v36
	s_nop 0
	v_add_u32_e32 v58, -1, v37
	v_fma_f32 v59, -v58, v37, v36
	v_cmp_ge_f32_e64 s[38:39], 0, v59
	v_add_u32_e32 v59, 1, v37
	s_nop 0
	v_cndmask_b32_e64 v58, v37, v58, s[38:39]
	v_fma_f32 v37, -v59, v37, v36
	v_cmp_lt_f32_e64 s[38:39], 0, v37
	s_nop 1
	v_cndmask_b32_e64 v37, v58, v59, s[38:39]
	v_mul_f32_e32 v58, 0x37800000, v37
	v_cndmask_b32_e32 v37, v37, v58, vcc
	v_cmp_class_f32_e32 vcc, v36, v196
	s_nop 1
	v_cndmask_b32_e32 v36, v37, v36, vcc
	v_div_scale_f32 v37, s[0:1], v36, v36, 1.0
	v_rcp_f32_e32 v58, v37
	s_nop 0
	v_fma_f32 v59, -v37, v58, 1.0
	v_fmac_f32_e32 v58, v59, v58
	v_div_scale_f32 v59, vcc, 1.0, v36, 1.0
	v_mul_f32_e32 v60, v59, v58
	v_fma_f32 v61, -v37, v60, v59
	v_fmac_f32_e32 v60, v61, v58
	v_fma_f32 v37, -v37, v60, v59
	v_div_fmas_f32 v37, v37, v58, v60
	v_div_fixup_f32 v62, v37, v36, 1.0
	v_lshlrev_b64 v[36:37], 13, v[188:189]
	v_lshl_add_u64 v[36:37], s[46:47], 0, v[36:37]
	v_pk_mul_f32 v[58:59], v[142:143], v[62:63] op_sel_hi:[1,0]
	v_pk_mul_f32 v[60:61], v[168:169], v[62:63] op_sel_hi:[1,0]
	v_lshl_add_u64 v[36:37], v[36:37], 0, v[38:39]
	v_pk_mul_f32 v[60:61], v[14:15], v[60:61]
	v_pk_mul_f32 v[58:59], v[12:13], v[58:59]
	global_store_dwordx4 v[36:37], v[58:61], off sc0 sc1
	s_nop 1
	v_pk_mul_f32 v[58:59], v[140:141], v[62:63] op_sel_hi:[1,0]
	v_pk_mul_f32 v[60:61], v[170:171], v[62:63] op_sel_hi:[1,0]
	v_pk_mul_f32 v[58:59], v[8:9], v[58:59]
	v_pk_mul_f32 v[60:61], v[10:11], v[60:61]
	global_store_dwordx4 v[36:37], v[58:61], off offset:16 sc0 sc1
	s_nop 1
	v_pk_mul_f32 v[58:59], v[172:173], v[62:63] op_sel_hi:[1,0]
	v_pk_mul_f32 v[60:61], v[164:165], v[62:63] op_sel_hi:[1,0]
	v_pk_mul_f32 v[58:59], v[4:5], v[58:59]
	v_pk_mul_f32 v[60:61], v[6:7], v[60:61]
	global_store_dwordx4 v[36:37], v[58:61], off offset:512 sc0 sc1
	s_nop 1
	v_pk_mul_f32 v[58:59], v[174:175], v[62:63] op_sel_hi:[1,0]
	v_pk_mul_f32 v[60:61], v[166:167], v[62:63] op_sel_hi:[1,0]
	v_pk_mul_f32 v[58:59], v[0:1], v[58:59]
	v_pk_mul_f32 v[60:61], v[2:3], v[60:61]
	global_store_dwordx4 v[36:37], v[58:61], off offset:528 sc0 sc1
	s_nop 1
	v_cvt_f32_u32_e32 v59, v63
	v_mov_b32_e32 v58, 0x358637bd
	s_nop 0
	v_fmac_f32_e32 v58, 0x36800000, v59
	v_cmp_gt_f32_e32 vcc, s66, v58
	v_mul_f32_e32 v59, 0x4f800000, v58
	s_nop 0
	v_cndmask_b32_e32 v58, v58, v59, vcc
	v_sqrt_f32_e32 v59, v58
	s_nop 0
	v_add_u32_e32 v60, -1, v59
	v_fma_f32 v61, -v60, v59, v58
	v_cmp_ge_f32_e64 s[38:39], 0, v61
	v_add_u32_e32 v61, 1, v59
	s_nop 0
	v_cndmask_b32_e64 v60, v59, v60, s[38:39]
	v_fma_f32 v59, -v61, v59, v58
	v_cmp_lt_f32_e64 s[38:39], 0, v59
	s_nop 1
	v_cndmask_b32_e64 v59, v60, v61, s[38:39]
	v_mul_f32_e32 v60, 0x37800000, v59
	v_cndmask_b32_e32 v59, v59, v60, vcc
	v_cmp_class_f32_e32 vcc, v58, v196
	s_nop 1
	v_cndmask_b32_e32 v58, v59, v58, vcc
	v_div_scale_f32 v59, s[0:1], v58, v58, 1.0
	v_rcp_f32_e32 v60, v59
	s_nop 0
	v_fma_f32 v61, -v59, v60, 1.0
	v_fmac_f32_e32 v60, v61, v60
	v_div_scale_f32 v61, vcc, 1.0, v58, 1.0
	v_mul_f32_e32 v62, v61, v60
	v_fma_f32 v63, -v59, v62, v61
	v_fmac_f32_e32 v62, v63, v60
	v_fma_f32 v59, -v59, v62, v61
	v_div_fmas_f32 v59, v59, v60, v62
	v_div_fixup_f32 v62, v59, v58, 1.0
	v_or_b32_e32 v58, 16, v188
	v_ashrrev_i32_e32 v59, 31, v58
	v_lshlrev_b64 v[58:59], 13, v[58:59]
	v_lshl_add_u64 v[58:59], s[46:47], 0, v[58:59]
	v_lshl_add_u64 v[64:65], v[58:59], 0, v[38:39]
	v_pk_mul_f32 v[58:59], v[160:161], v[62:63] op_sel_hi:[1,0]
	v_pk_mul_f32 v[60:61], v[152:153], v[62:63] op_sel_hi:[1,0]
	v_pk_mul_f32 v[58:59], v[12:13], v[58:59]
	v_pk_mul_f32 v[60:61], v[14:15], v[60:61]
	global_store_dwordx4 v[64:65], v[58:61], off sc0 sc1
	s_nop 1
	v_pk_mul_f32 v[58:59], v[162:163], v[62:63] op_sel_hi:[1,0]
	v_pk_mul_f32 v[60:61], v[154:155], v[62:63] op_sel_hi:[1,0]
	v_pk_mul_f32 v[58:59], v[8:9], v[58:59]
	v_pk_mul_f32 v[60:61], v[10:11], v[60:61]
	global_store_dwordx4 v[64:65], v[58:61], off offset:16 sc0 sc1
	s_nop 1
	v_pk_mul_f32 v[58:59], v[156:157], v[62:63] op_sel_hi:[1,0]
	v_pk_mul_f32 v[60:61], v[144:145], v[62:63] op_sel_hi:[1,0]
	v_pk_mul_f32 v[58:59], v[4:5], v[58:59]
	v_pk_mul_f32 v[60:61], v[6:7], v[60:61]
	global_store_dwordx4 v[64:65], v[58:61], off offset:512 sc0 sc1
	s_nop 1
	v_pk_mul_f32 v[58:59], v[158:159], v[62:63] op_sel_hi:[1,0]
	v_pk_mul_f32 v[60:61], v[146:147], v[62:63] op_sel_hi:[1,0]
	v_pk_mul_f32 v[58:59], v[0:1], v[58:59]
	v_pk_mul_f32 v[60:61], v[2:3], v[60:61]
	global_store_dwordx4 v[64:65], v[58:61], off offset:528 sc0 sc1
	s_nop 1
	v_mov_b32_e32 v58, 0x358637bd
	s_nop 0
	v_fmac_f32_e32 v58, 0x36800000, v52
	v_cmp_gt_f32_e32 vcc, s66, v58
	v_mul_f32_e32 v52, 0x4f800000, v58
	s_nop 0
	v_cndmask_b32_e32 v52, v58, v52, vcc
	v_sqrt_f32_e32 v58, v52
	s_nop 0
	v_add_u32_e32 v59, -1, v58
	v_fma_f32 v60, -v59, v58, v52
	v_cmp_ge_f32_e64 s[38:39], 0, v60
	v_add_u32_e32 v60, 1, v58
	s_nop 0
	v_cndmask_b32_e64 v59, v58, v59, s[38:39]
	v_fma_f32 v58, -v60, v58, v52
	v_cmp_lt_f32_e64 s[38:39], 0, v58
	s_nop 1
	v_cndmask_b32_e64 v58, v59, v60, s[38:39]
	v_mul_f32_e32 v59, 0x37800000, v58
	v_cndmask_b32_e32 v58, v58, v59, vcc
	v_cmp_class_f32_e32 vcc, v52, v196
	s_nop 1
	v_cndmask_b32_e32 v52, v58, v52, vcc
	v_div_scale_f32 v58, s[0:1], v52, v52, 1.0
	v_rcp_f32_e32 v59, v58
	s_nop 0
	v_fma_f32 v60, -v58, v59, 1.0
	v_fmac_f32_e32 v59, v60, v59
	v_div_scale_f32 v60, vcc, 1.0, v52, 1.0
	v_mul_f32_e32 v61, v60, v59
	v_fma_f32 v62, -v58, v61, v60
	v_fmac_f32_e32 v61, v62, v59
	v_fma_f32 v58, -v58, v61, v60
	v_div_fmas_f32 v58, v58, v59, v61
	v_div_fixup_f32 v52, v58, v52, 1.0
	v_or_b32_e32 v58, 32, v188
	v_ashrrev_i32_e32 v59, 31, v58
	v_lshlrev_b64 v[58:59], 13, v[58:59]
	v_lshl_add_u64 v[58:59], s[46:47], 0, v[58:59]
	v_lshl_add_u64 v[62:63], v[58:59], 0, v[38:39]
	s_waitcnt vmcnt(8)
;     __device__ __forceinline__ void operator()(pg8::Acc& acc, const pg8::Unit& u, int wr, int wc, int fr, int fq) const {
;     ...
; #pragma unroll
;         for (int ai = 0; ai < 2; ++ai)
; #pragma unroll
;             for (int m = 0; m < 4; ++m) {
;                 const float rr = pg8::rms_r(sv[ai * 4 + m]);
;                 float* op = out + (size_t)(row0 + ai * pg8::HALF + m * 16) * D + col0;
; #pragma unroll
;                 for (int bj = 0; bj < 2; ++bj) {
;                     *(f32x4*)(op + bj * pg8::HALF) = acc[ai][bj][m][0] * rr * gv[bj][0];
;                     *(f32x4*)(op + bj * pg8::HALF + 4) = acc[ai][bj][m][1] * rr * gv[bj][1];
;                 }
	v_pk_mul_f32 v[58:59], v[104:105], v[52:53] op_sel_hi:[1,0]
	v_pk_mul_f32 v[60:61], v[106:107], v[52:53] op_sel_hi:[1,0]
	v_pk_mul_f32 v[58:59], v[12:13], v[58:59]
	v_pk_mul_f32 v[60:61], v[14:15], v[60:61]
	global_store_dwordx4 v[62:63], v[58:61], off sc0 sc1
	s_nop 1
	v_pk_mul_f32 v[58:59], v[108:109], v[52:53] op_sel_hi:[1,0]
	v_pk_mul_f32 v[60:61], v[110:111], v[52:53] op_sel_hi:[1,0]
	v_pk_mul_f32 v[58:59], v[8:9], v[58:59]
	v_pk_mul_f32 v[60:61], v[10:11], v[60:61]
	global_store_dwordx4 v[62:63], v[58:61], off offset:16 sc0 sc1
	s_nop 1
	v_pk_mul_f32 v[58:59], v[136:137], v[52:53] op_sel_hi:[1,0]
	v_pk_mul_f32 v[60:61], v[132:133], v[52:53] op_sel_hi:[1,0]
	v_pk_mul_f32 v[58:59], v[4:5], v[58:59]
	v_pk_mul_f32 v[60:61], v[6:7], v[60:61]
	global_store_dwordx4 v[62:63], v[58:61], off offset:512 sc0 sc1
	s_nop 1
	v_pk_mul_f32 v[58:59], v[138:139], v[52:53] op_sel_hi:[1,0]
	v_pk_mul_f32 v[60:61], v[134:135], v[52:53] op_sel_hi:[1,0]
	v_pk_mul_f32 v[58:59], v[0:1], v[58:59]
	v_pk_mul_f32 v[60:61], v[2:3], v[60:61]
	v_mov_b32_e32 v52, 0x358637bd
	global_store_dwordx4 v[62:63], v[58:61], off offset:528 sc0 sc1
	s_nop 0
	v_fmac_f32_e32 v52, 0x36800000, v57
	v_cmp_gt_f32_e32 vcc, s66, v52
	v_mul_f32_e32 v57, 0x4f800000, v52
	s_nop 0
	v_cndmask_b32_e32 v52, v52, v57, vcc
	v_sqrt_f32_e32 v57, v52
	s_nop 0
	v_add_u32_e32 v58, -1, v57
	v_fma_f32 v59, -v58, v57, v52
	v_cmp_ge_f32_e64 s[38:39], 0, v59
	v_add_u32_e32 v59, 1, v57
	s_nop 0
	v_cndmask_b32_e64 v58, v57, v58, s[38:39]
	v_fma_f32 v57, -v59, v57, v52
	v_cmp_lt_f32_e64 s[38:39], 0, v57
	s_nop 1
	v_cndmask_b32_e64 v57, v58, v59, s[38:39]
	v_mul_f32_e32 v58, 0x37800000, v57
	v_cndmask_b32_e32 v57, v57, v58, vcc
	v_cmp_class_f32_e32 vcc, v52, v196
	s_nop 1
	v_cndmask_b32_e32 v52, v57, v52, vcc
	v_div_scale_f32 v57, s[0:1], v52, v52, 1.0
	v_rcp_f32_e32 v58, v57
	s_nop 0
	v_fma_f32 v59, -v57, v58, 1.0
	v_fmac_f32_e32 v58, v59, v58
	v_div_scale_f32 v59, vcc, 1.0, v52, 1.0
	v_mul_f32_e32 v60, v59, v58
	v_fma_f32 v61, -v57, v60, v59
	v_fmac_f32_e32 v60, v61, v58
	v_fma_f32 v57, -v57, v60, v59
	v_div_fmas_f32 v57, v57, v58, v60
	v_or_b32_e32 v58, 48, v188
	v_ashrrev_i32_e32 v59, 31, v58
	v_lshlrev_b64 v[58:59], 13, v[58:59]
	v_div_fixup_f32 v52, v57, v52, 1.0
	v_lshl_add_u64 v[58:59], s[46:47], 0, v[58:59]
	v_lshl_add_u64 v[38:39], v[58:59], 0, v[38:39]
	v_pk_mul_f32 v[58:59], v[128:129], v[52:53] op_sel_hi:[1,0]
	v_pk_mul_f32 v[60:61], v[120:121], v[52:53] op_sel_hi:[1,0]
	v_pk_mul_f32 v[58:59], v[12:13], v[58:59]
	v_pk_mul_f32 v[60:61], v[14:15], v[60:61]
	global_store_dwordx4 v[38:39], v[58:61], off sc0 sc1
	s_nop 1
	v_pk_mul_f32 v[58:59], v[130:131], v[52:53] op_sel_hi:[1,0]
	v_pk_mul_f32 v[60:61], v[122:123], v[52:53] op_sel_hi:[1,0]
	v_pk_mul_f32 v[58:59], v[8:9], v[58:59]
	v_pk_mul_f32 v[60:61], v[10:11], v[60:61]
	global_store_dwordx4 v[38:39], v[58:61], off offset:16 sc0 sc1
	s_nop 1
	v_pk_mul_f32 v[58:59], v[124:125], v[52:53] op_sel_hi:[1,0]
	v_pk_mul_f32 v[60:61], v[112:113], v[52:53] op_sel_hi:[1,0]
	v_pk_mul_f32 v[58:59], v[4:5], v[58:59]
	v_pk_mul_f32 v[60:61], v[6:7], v[60:61]
	global_store_dwordx4 v[38:39], v[58:61], off offset:512 sc0 sc1
	s_nop 1
	v_pk_mul_f32 v[58:59], v[126:127], v[52:53] op_sel_hi:[1,0]
	v_pk_mul_f32 v[60:61], v[114:115], v[52:53] op_sel_hi:[1,0]
	v_pk_mul_f32 v[58:59], v[0:1], v[58:59]
	v_pk_mul_f32 v[60:61], v[2:3], v[60:61]
	global_store_dwordx4 v[38:39], v[58:61], off offset:528 sc0 sc1
	v_cvt_f32_u32_e32 v39, v56
	v_mov_b32_e32 v38, 0x358637bd
	s_nop 0
	v_fmac_f32_e32 v38, 0x36800000, v39
	v_cmp_gt_f32_e32 vcc, s66, v38
	v_mul_f32_e32 v39, 0x4f800000, v38
	s_nop 0
	v_cndmask_b32_e32 v38, v38, v39, vcc
	v_sqrt_f32_e32 v39, v38
	s_nop 0
	v_add_u32_e32 v52, -1, v39
	v_fma_f32 v56, -v52, v39, v38
	v_cmp_ge_f32_e64 s[38:39], 0, v56
	v_add_u32_e32 v56, 1, v39
	s_nop 0
	v_cndmask_b32_e64 v52, v39, v52, s[38:39]
	v_fma_f32 v39, -v56, v39, v38
	v_cmp_lt_f32_e64 s[38:39], 0, v39
	s_nop 1
	v_cndmask_b32_e64 v39, v52, v56, s[38:39]
	v_mul_f32_e32 v52, 0x37800000, v39
	v_cndmask_b32_e32 v39, v39, v52, vcc
	v_cmp_class_f32_e32 vcc, v38, v196
	s_nop 1
	v_cndmask_b32_e32 v38, v39, v38, vcc
	v_div_scale_f32 v39, s[0:1], v38, v38, 1.0
	v_rcp_f32_e32 v52, v39
	s_mov_b64 s[0:1], 0x100000
	v_lshl_add_u64 v[60:61], v[36:37], 0, s[0:1]
	s_mov_b32 s0, 0x100000
	v_fma_f32 v56, -v39, v52, 1.0
	v_fmac_f32_e32 v52, v56, v52
	v_div_scale_f32 v56, vcc, 1.0, v38, 1.0
	v_mul_f32_e32 v57, v56, v52
	v_fma_f32 v58, -v39, v57, v56
	v_fmac_f32_e32 v57, v58, v52
	v_fma_f32 v39, -v39, v57, v56
	v_div_fmas_f32 v39, v39, v52, v57
	v_div_fixup_f32 v38, v39, v38, 1.0
	v_pk_mul_f32 v[56:57], v[72:73], v[38:39] op_sel_hi:[1,0]
	v_pk_mul_f32 v[58:59], v[74:75], v[38:39] op_sel_hi:[1,0]
	v_add_co_u32_e32 v62, vcc, s0, v36
	v_pk_mul_f32 v[58:59], v[14:15], v[58:59]
	v_pk_mul_f32 v[56:57], v[12:13], v[56:57]
	v_addc_co_u32_e32 v63, vcc, 0, v37, vcc
	global_store_dwordx4 v[62:63], v[56:59], off sc0 sc1
	s_nop 1
	v_pk_mul_f32 v[56:57], v[76:77], v[38:39] op_sel_hi:[1,0]
	v_pk_mul_f32 v[58:59], v[78:79], v[38:39] op_sel_hi:[1,0]
	v_pk_mul_f32 v[56:57], v[8:9], v[56:57]
	v_pk_mul_f32 v[58:59], v[10:11], v[58:59]
	global_store_dwordx4 v[60:61], v[56:59], off offset:16 sc0 sc1
	s_nop 1
	v_pk_mul_f32 v[56:57], v[116:117], v[38:39] op_sel_hi:[1,0]
	v_pk_mul_f32 v[58:59], v[100:101], v[38:39] op_sel_hi:[1,0]
	v_pk_mul_f32 v[56:57], v[4:5], v[56:57]
	v_pk_mul_f32 v[58:59], v[6:7], v[58:59]
	global_store_dwordx4 v[60:61], v[56:59], off offset:512 sc0 sc1
	s_nop 1
	v_pk_mul_f32 v[56:57], v[118:119], v[38:39] op_sel_hi:[1,0]
	v_pk_mul_f32 v[38:39], v[102:103], v[38:39] op_sel_hi:[1,0]
	v_pk_mul_f32 v[56:57], v[0:1], v[56:57]
;     __device__ __forceinline__ void operator()(pg8::Acc& acc, const pg8::Unit& u, int wr, int wc, int fr, int fq) const {
;     ...
; #pragma unroll
;         for (int ai = 0; ai < 2; ++ai)
; #pragma unroll
;             for (int m = 0; m < 4; ++m) {
;                 const float rr = pg8::rms_r(sv[ai * 4 + m]);
;                 float* op = out + (size_t)(row0 + ai * pg8::HALF + m * 16) * D + col0;
; #pragma unroll
;                 for (int bj = 0; bj < 2; ++bj) {
;                     *(f32x4*)(op + bj * pg8::HALF) = acc[ai][bj][m][0] * rr * gv[bj][0];
;                     *(f32x4*)(op + bj * pg8::HALF + 4) = acc[ai][bj][m][1] * rr * gv[bj][1];
;                 }
	v_pk_mul_f32 v[58:59], v[2:3], v[38:39]
	v_cvt_f32_u32_e32 v39, v55
	v_mov_b32_e32 v38, 0x358637bd
	global_store_dwordx4 v[60:61], v[56:59], off offset:528 sc0 sc1
	s_nop 0
	v_fmac_f32_e32 v38, 0x36800000, v39
	v_cmp_gt_f32_e32 vcc, s66, v38
	v_mul_f32_e32 v39, 0x4f800000, v38
	s_nop 0
	v_cndmask_b32_e32 v38, v38, v39, vcc
	v_sqrt_f32_e32 v39, v38
	s_nop 0
	v_add_u32_e32 v52, -1, v39
	v_fma_f32 v55, -v52, v39, v38
	v_cmp_ge_f32_e64 s[38:39], 0, v55
	v_add_u32_e32 v55, 1, v39
	s_nop 0
	v_cndmask_b32_e64 v52, v39, v52, s[38:39]
	v_fma_f32 v39, -v55, v39, v38
	v_cmp_lt_f32_e64 s[38:39], 0, v39
	s_nop 1
	v_cndmask_b32_e64 v39, v52, v55, s[38:39]
	v_mul_f32_e32 v52, 0x37800000, v39
	v_cndmask_b32_e32 v39, v39, v52, vcc
	v_cmp_class_f32_e32 vcc, v38, v196
	s_nop 1
	v_cndmask_b32_e32 v38, v39, v38, vcc
	v_div_scale_f32 v39, s[0:1], v38, v38, 1.0
	v_rcp_f32_e32 v52, v39
	s_mov_b64 s[0:1], 0x120000
	v_lshl_add_u64 v[60:61], v[36:37], 0, s[0:1]
	s_mov_b32 s0, 0x120000
	v_fma_f32 v55, -v39, v52, 1.0
	v_fmac_f32_e32 v52, v55, v52
	v_div_scale_f32 v55, vcc, 1.0, v38, 1.0
	v_mul_f32_e32 v56, v55, v52
	v_fma_f32 v57, -v39, v56, v55
	v_fmac_f32_e32 v56, v57, v52
	v_fma_f32 v39, -v39, v56, v55
	v_div_fmas_f32 v39, v39, v52, v56
	v_div_fixup_f32 v38, v39, v38, 1.0
	v_pk_mul_f32 v[56:57], v[96:97], v[38:39] op_sel_hi:[1,0]
	v_pk_mul_f32 v[58:59], v[88:89], v[38:39] op_sel_hi:[1,0]
	v_add_co_u32_e32 v62, vcc, s0, v36
	v_pk_mul_f32 v[58:59], v[14:15], v[58:59]
	v_pk_mul_f32 v[56:57], v[12:13], v[56:57]
	v_addc_co_u32_e32 v63, vcc, 0, v37, vcc
	global_store_dwordx4 v[62:63], v[56:59], off sc0 sc1
	s_nop 1
	v_pk_mul_f32 v[56:57], v[98:99], v[38:39] op_sel_hi:[1,0]
	v_pk_mul_f32 v[58:59], v[90:91], v[38:39] op_sel_hi:[1,0]
	v_pk_mul_f32 v[56:57], v[8:9], v[56:57]
	v_pk_mul_f32 v[58:59], v[10:11], v[58:59]
	global_store_dwordx4 v[60:61], v[56:59], off offset:16 sc0 sc1
	s_nop 1
	v_pk_mul_f32 v[56:57], v[92:93], v[38:39] op_sel_hi:[1,0]
	v_pk_mul_f32 v[58:59], v[80:81], v[38:39] op_sel_hi:[1,0]
	v_pk_mul_f32 v[56:57], v[4:5], v[56:57]
	v_pk_mul_f32 v[58:59], v[6:7], v[58:59]
	global_store_dwordx4 v[60:61], v[56:59], off offset:512 sc0 sc1
	s_nop 1
	v_pk_mul_f32 v[56:57], v[94:95], v[38:39] op_sel_hi:[1,0]
	v_pk_mul_f32 v[38:39], v[82:83], v[38:39] op_sel_hi:[1,0]
	v_pk_mul_f32 v[56:57], v[0:1], v[56:57]
	v_pk_mul_f32 v[58:59], v[2:3], v[38:39]
	v_cvt_f32_u32_e32 v39, v54
	v_mov_b32_e32 v38, 0x358637bd
	global_store_dwordx4 v[60:61], v[56:59], off offset:528 sc0 sc1
	s_nop 0
	v_fmac_f32_e32 v38, 0x36800000, v39
	v_cmp_gt_f32_e32 vcc, s66, v38
	v_mul_f32_e32 v39, 0x4f800000, v38
	s_nop 0
	v_cndmask_b32_e32 v38, v38, v39, vcc
	v_sqrt_f32_e32 v39, v38
	s_nop 0
	v_add_u32_e32 v52, -1, v39
	v_fma_f32 v54, -v52, v39, v38
	v_cmp_ge_f32_e64 s[38:39], 0, v54
	v_add_u32_e32 v54, 1, v39
	s_nop 0
	v_cndmask_b32_e64 v52, v39, v52, s[38:39]
	v_fma_f32 v39, -v54, v39, v38
	v_cmp_lt_f32_e64 s[38:39], 0, v39
	s_nop 1
	v_cndmask_b32_e64 v39, v52, v54, s[38:39]
	v_mul_f32_e32 v52, 0x37800000, v39
	v_cndmask_b32_e32 v39, v39, v52, vcc
	v_cmp_class_f32_e32 vcc, v38, v196
	s_nop 1
	v_cndmask_b32_e32 v38, v39, v38, vcc
	v_div_scale_f32 v39, s[0:1], v38, v38, 1.0
	v_rcp_f32_e32 v52, v39
	s_mov_b64 s[0:1], 0x140000
	v_fma_f32 v54, -v39, v52, 1.0
	v_fmac_f32_e32 v52, v54, v52
	v_div_scale_f32 v54, vcc, 1.0, v38, 1.0
	v_mul_f32_e32 v55, v54, v52
	v_fma_f32 v56, -v39, v55, v54
	v_fmac_f32_e32 v55, v56, v52
	v_fma_f32 v39, -v39, v55, v54
	v_div_fmas_f32 v39, v39, v52, v55
	v_div_fixup_f32 v38, v39, v38, 1.0
	v_lshl_add_u64 v[54:55], v[36:37], 0, s[0:1]
	s_mov_b32 s0, 0x140000
;     __device__ __forceinline__ void operator()(pg8::Acc& acc, const pg8::Unit& u, int wr, int wc, int fr, int fq) const {
;     ...
; #pragma unroll
;         for (int ai = 0; ai < 2; ++ai)
; #pragma unroll
;             for (int m = 0; m < 4; ++m) {
;                 const float rr = pg8::rms_r(sv[ai * 4 + m]);
;                 float* op = out + (size_t)(row0 + ai * pg8::HALF + m * 16) * D + col0;
; #pragma unroll
;                 for (int bj = 0; bj < 2; ++bj) {
;                     *(f32x4*)(op + bj * pg8::HALF) = acc[ai][bj][m][0] * rr * gv[bj][0];
;                     *(f32x4*)(op + bj * pg8::HALF + 4) = acc[ai][bj][m][1] * rr * gv[bj][1];
;                 }
	v_pk_mul_f32 v[24:25], v[24:25], v[38:39] op_sel_hi:[1,0]
	v_pk_mul_f32 v[26:27], v[26:27], v[38:39] op_sel_hi:[1,0]
	v_add_co_u32_e32 v56, vcc, s0, v36
	v_pk_mul_f32 v[26:27], v[14:15], v[26:27]
	v_pk_mul_f32 v[24:25], v[12:13], v[24:25]
	v_addc_co_u32_e32 v57, vcc, 0, v37, vcc
	global_store_dwordx4 v[56:57], v[24:27], off sc0 sc1
	v_pk_mul_f32 v[16:17], v[16:17], v[38:39] op_sel_hi:[1,0]
	s_nop 0
	v_pk_mul_f32 v[24:25], v[28:29], v[38:39] op_sel_hi:[1,0]
	v_pk_mul_f32 v[26:27], v[30:31], v[38:39] op_sel_hi:[1,0]
	v_pk_mul_f32 v[24:25], v[8:9], v[24:25]
	v_pk_mul_f32 v[26:27], v[10:11], v[26:27]
	global_store_dwordx4 v[54:55], v[24:27], off offset:16 sc0 sc1
	s_nop 1
	v_pk_mul_f32 v[24:25], v[48:49], v[38:39] op_sel_hi:[1,0]
	s_nop 0
	v_pk_mul_f32 v[26:27], v[6:7], v[24:25]
	v_pk_mul_f32 v[24:25], v[4:5], v[16:17]
	v_pk_mul_f32 v[16:17], v[20:21], v[38:39] op_sel_hi:[1,0]
	global_store_dwordx4 v[54:55], v[24:27], off offset:512 sc0 sc1
	v_pk_mul_f32 v[20:21], v[50:51], v[38:39] op_sel_hi:[1,0]
	s_nop 0
	v_pk_mul_f32 v[24:25], v[0:1], v[16:17]
	v_cvt_f32_u32_e32 v17, v53
	v_pk_mul_f32 v[26:27], v[2:3], v[20:21]
	v_mov_b32_e32 v16, 0x358637bd
	global_store_dwordx4 v[54:55], v[24:27], off offset:528 sc0 sc1
	s_nop 0
	v_fmac_f32_e32 v16, 0x36800000, v17
	v_cmp_gt_f32_e32 vcc, s66, v16
	v_mul_f32_e32 v17, 0x4f800000, v16
	s_nop 0
	v_cndmask_b32_e32 v16, v16, v17, vcc
	v_sqrt_f32_e32 v17, v16
	s_nop 0
	v_add_u32_e32 v20, -1, v17
	v_fma_f32 v21, -v20, v17, v16
	v_cmp_ge_f32_e64 s[38:39], 0, v21
	v_add_u32_e32 v21, 1, v17
	s_nop 0
	v_cndmask_b32_e64 v20, v17, v20, s[38:39]
	v_fma_f32 v17, -v21, v17, v16
	v_cmp_lt_f32_e64 s[38:39], 0, v17
	s_nop 1
	v_cndmask_b32_e64 v17, v20, v21, s[38:39]
	v_mul_f32_e32 v20, 0x37800000, v17
	v_cndmask_b32_e32 v17, v17, v20, vcc
	v_cmp_class_f32_e32 vcc, v16, v196
	s_nop 1
	v_cndmask_b32_e32 v16, v17, v16, vcc
	v_div_scale_f32 v17, s[0:1], v16, v16, 1.0
	v_rcp_f32_e32 v20, v17
	s_mov_b64 s[0:1], 0x160000
	v_fma_f32 v21, -v17, v20, 1.0
	v_fmac_f32_e32 v20, v21, v20
	v_div_scale_f32 v21, vcc, 1.0, v16, 1.0
	v_mul_f32_e32 v24, v21, v20
	v_fma_f32 v25, -v17, v24, v21
	v_fmac_f32_e32 v24, v25, v20
	v_fma_f32 v17, -v17, v24, v21
	v_div_fmas_f32 v17, v17, v20, v24
	v_div_fixup_f32 v16, v17, v16, 1.0
	v_lshl_add_u64 v[20:21], v[36:37], 0, s[0:1]
	v_pk_mul_f32 v[18:19], v[18:19], v[16:17] op_sel_hi:[1,0]
	s_mov_b32 s0, 0x160000
	v_pk_mul_f32 v[24:25], v[40:41], v[16:17] op_sel_hi:[1,0]
	v_pk_mul_f32 v[12:13], v[12:13], v[18:19]
	v_add_co_u32_e32 v18, vcc, s0, v36
	v_pk_mul_f32 v[14:15], v[14:15], v[24:25]
	s_nop 0
	v_addc_co_u32_e32 v19, vcc, 0, v37, vcc
	global_store_dwordx4 v[18:19], v[12:15], off sc0 sc1
	s_mov_b64 s[0:1], -1
	s_andn2_b64 vcc, exec, s[62:63]
	v_pk_mul_f32 v[12:13], v[22:23], v[16:17] op_sel_hi:[1,0]
	v_pk_mul_f32 v[14:15], v[42:43], v[16:17] op_sel_hi:[1,0]
	v_pk_mul_f32 v[8:9], v[8:9], v[12:13]
	v_pk_mul_f32 v[10:11], v[10:11], v[14:15]
	global_store_dwordx4 v[20:21], v[8:11], off offset:16 sc0 sc1
	s_nop 1
	v_pk_mul_f32 v[8:9], v[44:45], v[16:17] op_sel_hi:[1,0]
	v_pk_mul_f32 v[10:11], v[32:33], v[16:17] op_sel_hi:[1,0]
	v_pk_mul_f32 v[4:5], v[4:5], v[8:9]
	v_pk_mul_f32 v[6:7], v[6:7], v[10:11]
	global_store_dwordx4 v[20:21], v[4:7], off offset:512 sc0 sc1
	s_nop 1
	v_pk_mul_f32 v[4:5], v[46:47], v[16:17] op_sel_hi:[1,0]
	v_pk_mul_f32 v[6:7], v[34:35], v[16:17] op_sel_hi:[1,0]
	v_pk_mul_f32 v[0:1], v[0:1], v[4:5]
	v_pk_mul_f32 v[2:3], v[2:3], v[6:7]
	global_store_dwordx4 v[20:21], v[0:3], off offset:528 sc0 sc1
	s_cbranch_vccnz .LBB0_991
	s_andn2_b64 vcc, exec, s[10:11]
	s_cbranch_vccnz .LBB0_990
	s_barrier
	s_branch .LBB0_990
